# scalar-side LDS-DMA addressing extended to one GEMM2 (K=2048) K-loop: 14 of 16 adds (the per-lane 64-bit base pair of segment 1 stays), LDS-offset temp moved off the B base pair
# baseline (speedup 1.0000x reference)
.LBB0_426:
	s_add_u32 s3, s54, s58
	s_addc_u32 s60, s55, s59
	s_add_u32 s3, s3, 0x100
	s_addc_u32 s60, s60, 0
	s_add_u32 s66, s21, s58
	s_addc_u32 s67, s62, s59
	s_add_i32 s85, 0, 0x10000
	s_cmpk_eq_i32 s58, 0xf00
	s_cselect_b32 s61, s53, s60
	s_cselect_b32 s60, vcc_lo, s3
	v_add_u32_e32 v146, s85, v144
	s_cselect_b32 s67, s51, s67
	s_cselect_b32 s66, vcc_hi, s66
	s_add_i32 s3, 0, 0x14000
	ds_read_b128 v[150:153], v146
	ds_read_b128 v[164:167], v146 offset:1024
	ds_read_b128 v[178:181], v146 offset:2048
	ds_read_b128 v[182:185], v146 offset:3072
	v_add_u32_e32 v146, s3, v144
	ds_read_b128 v[186:189], v146
	ds_read_b128 v[190:193], v146 offset:1024
	ds_read_b128 v[194:197], v146 offset:2048
	ds_read_b128 v[198:201], v146 offset:3072
	v_lshl_add_u64 v[146:147], v[140:141], 0, s[58:59]
	s_add_i32 m0, s16, 0xc000
	ds_read_b128 v[202:205], v145
	ds_read_b128 v[206:209], v145 offset:1024
	ds_read_b128 v[210:213], v145 offset:2048
	ds_read_b128 v[214:217], v145 offset:3072
	ds_read_b128 v[218:221], v145 offset:4096
	ds_read_b128 v[222:225], v145 offset:5120
	ds_read_b128 v[226:229], v145 offset:6144
	ds_read_b128 v[230:233], v145 offset:7168
	global_load_lds_dwordx4 v[146:147], off
	v_lshl_add_u64 v[146:147], v[142:143], 0, s[58:59]
	s_add_i32 m0, s16, 0xe000
	s_nop 0
	global_load_lds_dwordx4 v[146:147], off
	s_waitcnt vmcnt(8)
	s_waitcnt lgkmcnt(0)
	v_mfma_f32_16x16x32_bf16 v[28:31], v[150:153], v[202:205], v[28:31]
	v_mfma_f32_16x16x32_bf16 v[20:23], v[178:181], v[202:205], v[20:23]
	v_mfma_f32_16x16x32_bf16 v[32:35], v[150:153], v[210:213], v[32:35]
	v_mfma_f32_16x16x32_bf16 v[24:27], v[178:181], v[210:213], v[24:27]
	s_barrier
	s_setprio 1
	s_waitcnt lgkmcnt(0)
	v_mfma_f32_16x16x32_bf16 v[60:63], v[150:153], v[218:221], v[60:63]
	v_mfma_f32_16x16x32_bf16 v[52:55], v[178:181], v[218:221], v[52:55]
	v_mfma_f32_16x16x32_bf16 v[64:67], v[150:153], v[226:229], v[64:67]
	v_mfma_f32_16x16x32_bf16 v[56:59], v[178:181], v[226:229], v[56:59]
	v_mfma_f32_16x16x32_bf16 v[28:31], v[164:167], v[206:209], v[28:31]
	v_mfma_f32_16x16x32_bf16 v[20:23], v[182:185], v[206:209], v[20:23]
	v_mfma_f32_16x16x32_bf16 v[32:35], v[164:167], v[214:217], v[32:35]
	v_mfma_f32_16x16x32_bf16 v[24:27], v[182:185], v[214:217], v[24:27]
	v_mfma_f32_16x16x32_bf16 v[60:63], v[164:167], v[222:225], v[60:63]
	v_mfma_f32_16x16x32_bf16 v[52:55], v[182:185], v[222:225], v[52:55]
	v_mfma_f32_16x16x32_bf16 v[64:67], v[164:167], v[230:233], v[64:67]
	v_mfma_f32_16x16x32_bf16 v[56:59], v[182:185], v[230:233], v[56:59]
	s_setprio 0
	s_setprio 1
	v_mfma_f32_16x16x32_bf16 v[12:15], v[186:189], v[202:205], v[12:15]
	v_mfma_f32_16x16x32_bf16 v[4:7], v[194:197], v[202:205], v[4:7]
	v_mfma_f32_16x16x32_bf16 v[16:19], v[186:189], v[210:213], v[16:19]
	v_mfma_f32_16x16x32_bf16 v[8:11], v[194:197], v[210:213], v[8:11]
	v_mfma_f32_16x16x32_bf16 v[44:47], v[186:189], v[218:221], v[44:47]
	v_mfma_f32_16x16x32_bf16 v[36:39], v[194:197], v[218:221], v[36:39]
	v_mfma_f32_16x16x32_bf16 v[48:51], v[186:189], v[226:229], v[48:51]
	v_mfma_f32_16x16x32_bf16 v[40:43], v[194:197], v[226:229], v[40:43]
	v_mfma_f32_16x16x32_bf16 v[12:15], v[190:193], v[206:209], v[12:15]
	v_mfma_f32_16x16x32_bf16 v[4:7], v[198:201], v[206:209], v[4:7]
	v_mfma_f32_16x16x32_bf16 v[16:19], v[190:193], v[214:217], v[16:19]
	v_mfma_f32_16x16x32_bf16 v[8:11], v[198:201], v[214:217], v[8:11]
	v_mfma_f32_16x16x32_bf16 v[44:47], v[190:193], v[222:225], v[44:47]
	v_mfma_f32_16x16x32_bf16 v[36:39], v[198:201], v[222:225], v[36:39]
	v_mfma_f32_16x16x32_bf16 v[48:51], v[190:193], v[230:233], v[48:51]
	v_mfma_f32_16x16x32_bf16 v[40:43], v[198:201], v[230:233], v[40:43]
	s_setprio 0
	s_barrier
	s_add_i32 s85, s85, s15
	s_mov_b32 m0, s85
	ds_read_b128 v[202:205], v145 offset:16384
	ds_read_b128 v[206:209], v145 offset:17408
	ds_read_b128 v[210:213], v145 offset:18432
	ds_read_b128 v[214:217], v145 offset:19456
	ds_read_b128 v[218:221], v145 offset:20480
	ds_read_b128 v[222:225], v145 offset:21504
	ds_read_b128 v[226:229], v145 offset:22528
	ds_read_b128 v[230:233], v145 offset:23552
	global_load_lds_dwordx4 v2, s[66:67]
	s_add_i32 m0, s85, 0x2000
	s_add_i32 s3, s3, s15
	global_load_lds_dwordx4 v132, s[66:67]
	s_mov_b32 m0, s3
	s_nop 0
	global_load_lds_dwordx4 v134, s[66:67]
	s_add_i32 m0, s3, 0x2000
	s_nop 0
	global_load_lds_dwordx4 v0, s[66:67]
	s_mov_b32 m0, s16
	s_nop 0
	global_load_lds_dwordx4 v2, s[60:61]
	s_mov_b32 m0, s17
	s_nop 0
	global_load_lds_dwordx4 v132, s[60:61]
	s_waitcnt vmcnt(8)
	s_waitcnt lgkmcnt(0)
	v_mfma_f32_16x16x32_bf16 v[92:95], v[150:153], v[202:205], v[92:95]
	v_mfma_f32_16x16x32_bf16 v[84:87], v[178:181], v[202:205], v[84:87]
	v_mfma_f32_16x16x32_bf16 v[96:99], v[150:153], v[210:213], v[96:99]
	v_mfma_f32_16x16x32_bf16 v[88:91], v[178:181], v[210:213], v[88:91]
	s_barrier
	s_setprio 1
	s_waitcnt lgkmcnt(0)
	v_mfma_f32_16x16x32_bf16 v[124:127], v[150:153], v[218:221], v[124:127]
	v_mfma_f32_16x16x32_bf16 v[116:119], v[178:181], v[218:221], v[116:119]
	v_mfma_f32_16x16x32_bf16 v[128:131], v[150:153], v[226:229], v[128:131]
	v_mfma_f32_16x16x32_bf16 v[120:123], v[178:181], v[226:229], v[120:123]
	v_mfma_f32_16x16x32_bf16 v[92:95], v[164:167], v[206:209], v[92:95]
	v_mfma_f32_16x16x32_bf16 v[84:87], v[182:185], v[206:209], v[84:87]
	v_mfma_f32_16x16x32_bf16 v[96:99], v[164:167], v[214:217], v[96:99]
	v_mfma_f32_16x16x32_bf16 v[88:91], v[182:185], v[214:217], v[88:91]
	v_mfma_f32_16x16x32_bf16 v[124:127], v[164:167], v[222:225], v[124:127]
	v_mfma_f32_16x16x32_bf16 v[116:119], v[182:185], v[222:225], v[116:119]
	v_mfma_f32_16x16x32_bf16 v[128:131], v[164:167], v[230:233], v[128:131]
	v_mfma_f32_16x16x32_bf16 v[120:123], v[182:185], v[230:233], v[120:123]
	s_setprio 0
	s_setprio 1
	v_mfma_f32_16x16x32_bf16 v[76:79], v[186:189], v[202:205], v[76:79]
	v_mfma_f32_16x16x32_bf16 v[68:71], v[194:197], v[202:205], v[68:71]
	v_mfma_f32_16x16x32_bf16 v[80:83], v[186:189], v[210:213], v[80:83]
	v_mfma_f32_16x16x32_bf16 v[72:75], v[194:197], v[210:213], v[72:75]
	v_mfma_f32_16x16x32_bf16 v[108:111], v[186:189], v[218:221], v[108:111]
	v_mfma_f32_16x16x32_bf16 v[100:103], v[194:197], v[218:221], v[100:103]
	v_mfma_f32_16x16x32_bf16 v[112:115], v[186:189], v[226:229], v[112:115]
	v_mfma_f32_16x16x32_bf16 v[104:107], v[194:197], v[226:229], v[104:107]
	v_mfma_f32_16x16x32_bf16 v[76:79], v[190:193], v[206:209], v[76:79]
	v_mfma_f32_16x16x32_bf16 v[68:71], v[198:201], v[206:209], v[68:71]
	v_mfma_f32_16x16x32_bf16 v[80:83], v[190:193], v[214:217], v[80:83]
	v_mfma_f32_16x16x32_bf16 v[72:75], v[198:201], v[214:217], v[72:75]
	v_mfma_f32_16x16x32_bf16 v[108:111], v[190:193], v[222:225], v[108:111]
	v_mfma_f32_16x16x32_bf16 v[100:103], v[198:201], v[222:225], v[100:103]
	v_mfma_f32_16x16x32_bf16 v[112:115], v[190:193], v[230:233], v[112:115]
	v_mfma_f32_16x16x32_bf16 v[104:107], v[198:201], v[230:233], v[104:107]
	s_setprio 0
	s_barrier
	s_add_i32 s3, 0, 0x18000
	v_add_u32_e32 v149, s3, v144
	s_add_i32 s98, 0, 0x1c000
	ds_read_b128 v[150:153], v149
	ds_read_b128 v[164:167], v149 offset:1024
	ds_read_b128 v[178:181], v149 offset:2048
	ds_read_b128 v[182:185], v149 offset:3072
	v_add_u32_e32 v149, s98, v144
	ds_read_b128 v[186:189], v149
	ds_read_b128 v[190:193], v149 offset:1024
	ds_read_b128 v[194:197], v149 offset:2048
	ds_read_b128 v[198:201], v149 offset:3072
	s_add_u32 s60, s60, 0x80000
	s_addc_u32 s61, s61, 0
	s_mov_b32 m0, s28
	ds_read_b128 v[202:205], v145 offset:32768
	ds_read_b128 v[206:209], v145 offset:33792
	ds_read_b128 v[210:213], v145 offset:34816
	ds_read_b128 v[214:217], v145 offset:35840
	ds_read_b128 v[218:221], v145 offset:36864
	ds_read_b128 v[222:225], v145 offset:37888
	ds_read_b128 v[226:229], v145 offset:38912
	ds_read_b128 v[230:233], v145 offset:39936
	global_load_lds_dwordx4 v2, s[60:61]
	s_mov_b32 m0, s95
	s_nop 0
	global_load_lds_dwordx4 v132, s[60:61]
	s_waitcnt vmcnt(8)
	s_waitcnt lgkmcnt(0)
	v_mfma_f32_16x16x32_bf16 v[28:31], v[150:153], v[202:205], v[28:31]
	v_mfma_f32_16x16x32_bf16 v[20:23], v[178:181], v[202:205], v[20:23]
	v_mfma_f32_16x16x32_bf16 v[32:35], v[150:153], v[210:213], v[32:35]
	v_mfma_f32_16x16x32_bf16 v[24:27], v[178:181], v[210:213], v[24:27]
	s_barrier
	s_setprio 1
	s_waitcnt lgkmcnt(0)
	v_mfma_f32_16x16x32_bf16 v[60:63], v[150:153], v[218:221], v[60:63]
	v_mfma_f32_16x16x32_bf16 v[52:55], v[178:181], v[218:221], v[52:55]
	v_mfma_f32_16x16x32_bf16 v[64:67], v[150:153], v[226:229], v[64:67]
	v_mfma_f32_16x16x32_bf16 v[56:59], v[178:181], v[226:229], v[56:59]
	v_mfma_f32_16x16x32_bf16 v[28:31], v[164:167], v[206:209], v[28:31]
	v_mfma_f32_16x16x32_bf16 v[20:23], v[182:185], v[206:209], v[20:23]
	v_mfma_f32_16x16x32_bf16 v[32:35], v[164:167], v[214:217], v[32:35]
	v_mfma_f32_16x16x32_bf16 v[24:27], v[182:185], v[214:217], v[24:27]
	v_mfma_f32_16x16x32_bf16 v[60:63], v[164:167], v[222:225], v[60:63]
	v_mfma_f32_16x16x32_bf16 v[52:55], v[182:185], v[222:225], v[52:55]
	v_mfma_f32_16x16x32_bf16 v[64:67], v[164:167], v[230:233], v[64:67]
	v_mfma_f32_16x16x32_bf16 v[56:59], v[182:185], v[230:233], v[56:59]
	s_setprio 0
	s_setprio 1
	v_mfma_f32_16x16x32_bf16 v[12:15], v[186:189], v[202:205], v[12:15]
	v_mfma_f32_16x16x32_bf16 v[4:7], v[194:197], v[202:205], v[4:7]
	v_mfma_f32_16x16x32_bf16 v[16:19], v[186:189], v[210:213], v[16:19]
	v_mfma_f32_16x16x32_bf16 v[8:11], v[194:197], v[210:213], v[8:11]
	v_mfma_f32_16x16x32_bf16 v[44:47], v[186:189], v[218:221], v[44:47]
	v_mfma_f32_16x16x32_bf16 v[36:39], v[194:197], v[218:221], v[36:39]
	v_mfma_f32_16x16x32_bf16 v[48:51], v[186:189], v[226:229], v[48:51]
	v_mfma_f32_16x16x32_bf16 v[40:43], v[194:197], v[226:229], v[40:43]
	v_mfma_f32_16x16x32_bf16 v[12:15], v[190:193], v[206:209], v[12:15]
	v_mfma_f32_16x16x32_bf16 v[4:7], v[198:201], v[206:209], v[4:7]
	v_mfma_f32_16x16x32_bf16 v[16:19], v[190:193], v[214:217], v[16:19]
	v_mfma_f32_16x16x32_bf16 v[8:11], v[198:201], v[214:217], v[8:11]
	v_mfma_f32_16x16x32_bf16 v[44:47], v[190:193], v[222:225], v[44:47]
	v_mfma_f32_16x16x32_bf16 v[36:39], v[198:201], v[222:225], v[36:39]
	v_mfma_f32_16x16x32_bf16 v[48:51], v[190:193], v[230:233], v[48:51]
	v_mfma_f32_16x16x32_bf16 v[40:43], v[198:201], v[230:233], v[40:43]
	s_setprio 0
	s_barrier
	s_add_i32 s3, s3, s15
	s_add_u32 s66, s66, 0x80
	s_addc_u32 s67, s67, 0
	s_add_u32 s60, s60, 0xfff80080
	s_addc_u32 s61, s61, -1
	s_mov_b32 m0, s3
	ds_read_b128 v[202:205], v145 offset:49152
	ds_read_b128 v[206:209], v145 offset:50176
	ds_read_b128 v[210:213], v145 offset:51200
	ds_read_b128 v[214:217], v145 offset:52224
	ds_read_b128 v[218:221], v145 offset:53248
	ds_read_b128 v[222:225], v145 offset:54272
	ds_read_b128 v[226:229], v145 offset:55296
	ds_read_b128 v[230:233], v145 offset:56320
	global_load_lds_dwordx4 v2, s[66:67]
	s_add_i32 m0, s3, 0x2000
	s_add_i32 s3, s98, s15
	global_load_lds_dwordx4 v132, s[66:67]
	s_mov_b32 m0, s3
	s_nop 0
	global_load_lds_dwordx4 v134, s[66:67]
	s_add_i32 m0, s3, 0x2000
	s_nop 0
	global_load_lds_dwordx4 v0, s[66:67]
	s_mov_b32 m0, s97
	s_nop 0
	global_load_lds_dwordx4 v2, s[60:61]
	s_mov_b32 m0, s12
	s_nop 0
	global_load_lds_dwordx4 v132, s[60:61]
	s_waitcnt vmcnt(8)
	s_waitcnt lgkmcnt(0)
	v_mfma_f32_16x16x32_bf16 v[92:95], v[150:153], v[202:205], v[92:95]
	v_mfma_f32_16x16x32_bf16 v[84:87], v[178:181], v[202:205], v[84:87]
	v_mfma_f32_16x16x32_bf16 v[96:99], v[150:153], v[210:213], v[96:99]
	v_mfma_f32_16x16x32_bf16 v[88:91], v[178:181], v[210:213], v[88:91]
	s_barrier
	s_setprio 1
	s_waitcnt lgkmcnt(0)
	v_mfma_f32_16x16x32_bf16 v[124:127], v[150:153], v[218:221], v[124:127]
	v_mfma_f32_16x16x32_bf16 v[116:119], v[178:181], v[218:221], v[116:119]
	v_mfma_f32_16x16x32_bf16 v[128:131], v[150:153], v[226:229], v[128:131]
	v_mfma_f32_16x16x32_bf16 v[120:123], v[178:181], v[226:229], v[120:123]
	v_mfma_f32_16x16x32_bf16 v[92:95], v[164:167], v[206:209], v[92:95]
	v_mfma_f32_16x16x32_bf16 v[84:87], v[182:185], v[206:209], v[84:87]
	v_mfma_f32_16x16x32_bf16 v[96:99], v[164:167], v[214:217], v[96:99]
	v_mfma_f32_16x16x32_bf16 v[88:91], v[182:185], v[214:217], v[88:91]
	v_mfma_f32_16x16x32_bf16 v[124:127], v[164:167], v[222:225], v[124:127]
	v_mfma_f32_16x16x32_bf16 v[116:119], v[182:185], v[222:225], v[116:119]
	v_mfma_f32_16x16x32_bf16 v[128:131], v[164:167], v[230:233], v[128:131]
	v_mfma_f32_16x16x32_bf16 v[120:123], v[182:185], v[230:233], v[120:123]
	s_setprio 0
	s_setprio 1
	v_mfma_f32_16x16x32_bf16 v[76:79], v[186:189], v[202:205], v[76:79]
	v_mfma_f32_16x16x32_bf16 v[68:71], v[194:197], v[202:205], v[68:71]
	v_mfma_f32_16x16x32_bf16 v[80:83], v[186:189], v[210:213], v[80:83]
	v_mfma_f32_16x16x32_bf16 v[72:75], v[194:197], v[210:213], v[72:75]
	v_mfma_f32_16x16x32_bf16 v[108:111], v[186:189], v[218:221], v[108:111]
	v_mfma_f32_16x16x32_bf16 v[100:103], v[194:197], v[218:221], v[100:103]
	v_mfma_f32_16x16x32_bf16 v[112:115], v[186:189], v[226:229], v[112:115]
	v_mfma_f32_16x16x32_bf16 v[104:107], v[194:197], v[226:229], v[104:107]
	v_mfma_f32_16x16x32_bf16 v[76:79], v[190:193], v[206:209], v[76:79]
	v_mfma_f32_16x16x32_bf16 v[68:71], v[198:201], v[206:209], v[68:71]
	v_mfma_f32_16x16x32_bf16 v[80:83], v[190:193], v[214:217], v[80:83]
	v_mfma_f32_16x16x32_bf16 v[72:75], v[198:201], v[214:217], v[72:75]
	v_mfma_f32_16x16x32_bf16 v[108:111], v[190:193], v[222:225], v[108:111]
	v_mfma_f32_16x16x32_bf16 v[100:103], v[198:201], v[222:225], v[100:103]
	v_mfma_f32_16x16x32_bf16 v[112:115], v[190:193], v[230:233], v[112:115]
	v_mfma_f32_16x16x32_bf16 v[104:107], v[198:201], v[230:233], v[104:107]
	s_setprio 0
	s_barrier
	s_add_i32 s2, s2, 2
	s_add_u32 s58, s58, 0x100
	s_addc_u32 s59, s59, 0
	s_cmp_gt_u32 s2, 29
	s_cbranch_scc0 .LBB0_426
	s_and_b64 vcc, exec, s[48:49]
	s_cbranch_vccz .LBB0_429
	s_barrier

.LBB0_738:
	s_waitcnt vmcnt(0) lgkmcnt(0)
	s_mov_b32 s79, 0x3e38aa3b
	s_mov_b32 s77, 0xc000
	s_mov_b32 s78, 0xffffc000
	v_readlane_b32 s1, v253, 23
	v_readfirstlane_b32 s0, v170
	s_nop 3
	s_lshr_b32 s0, s0, 6
	s_and_b32 s74, s1, 7
	s_lshl_b32 s74, s74, 5
	s_lshr_b32 s75, s1, 3
	s_add_u32 s74, s74, s75
	s_lshl_b32 s74, s74, 3
	s_and_b32 s4, s74, 31
	s_lshr_b32 s75, s74, 5
	s_and_b32 s5, s75, 0
	s_lshr_b32 s75, s75, 0
	s_and_b32 s3, s75, 3
	s_lshr_b32 s2, s75, 2
	s_sub_u32 s6, 8, s0
	s_lshl_b32 s70, s0, 10
	s_lshl_b32 s74, s2, 21
	s_lshl_b32 s75, s3, 19
	s_add_u32 s74, s74, s75
	s_add_u32 s34, s40, s74
	s_addc_u32 s35, s41, 0
	s_mov_b32 s30, s34
	s_mov_b32 s31, s35
	s_lshl_b32 s74, s2, 16
	s_lshl_b32 s75, s3, 14
	s_add_u32 s74, s74, s75
	s_add_u32 s74, s74, 0xc000000
	s_add_u32 s58, s42, s74
	s_addc_u32 s59, s43, 0
	s_add_u32 s74, s2, 0
	s_lshl_b32 s74, s74, 2
	s_add_u32 s74, s74, s3
	s_lshl_b32 s74, s74, 19
	s_add_u32 s60, s42, s74
	s_addc_u32 s61, s43, 0
	s_lshl_b32 s74, s2, 6
	s_add_u32 s74, s74, 0
	s_lshl_b32 s74, s74, 15
	s_lshl_b32 s75, s3, 13
	s_add_u32 s74, s74, s75
	s_add_u32 s74, s74, 0x6000000
	s_add_u32 s64, s42, s74
	s_addc_u32 s65, s43, 0
	v_and_b32_e32 v141, 63, v170
	v_and_b32_e32 v241, 15, v141
	v_lshrrev_b32_e32 v242, 4, v141
	v_mov_b32_e32 v244, 0xf149f2ca
	v_mov_b32_e32 v248, 0
	v_mov_b32_e32 v249, 0
	v_lshrrev_b32_e32 v142, 1, v241
	v_xor_b32_e32 v142, v142, v242
	v_lshlrev_b32_e32 v142, 4, v142
	v_lshl_add_u32 v142, v241, 7, v142
	s_lshl_b32 s74, s0, 11
	v_add_u32_e32 v230, s74, v142
	v_xor_b32_e32 v231, 64, v230
	v_lshrrev_b32_e32 v142, 1, v242
	v_xor_b32_e32 v243, v142, v241
	v_and_b32_e32 v142, 1, v242
	v_lshlrev_b32_e32 v142, 3, v142
	v_lshl_add_u32 v142, v241, 8, v142
	v_add_u32_e32 v142, 0x10000, v142
	s_add_u32 s74, s0, 0
	s_and_b32 s75, s74, 7
	s_lshl_b32 s75, s75, 1
	s_lshr_b32 s74, s74, 3
	s_lshl_b32 s74, s74, 14
	v_xor_b32_e32 v143, s75, v243
	v_lshl_add_u32 v143, v143, 4, v142
	v_add_u32_e32 v221, s74, v143
	s_add_u32 s74, s0, 1
	s_and_b32 s75, s74, 7
	s_lshl_b32 s75, s75, 1
	s_lshr_b32 s74, s74, 3
	s_lshl_b32 s74, s74, 14
	v_xor_b32_e32 v143, s75, v243
	v_lshl_add_u32 v143, v143, 4, v142
	v_add_u32_e32 v222, s74, v143
	s_add_u32 s74, s0, 2
	s_and_b32 s75, s74, 7
	s_lshl_b32 s75, s75, 1
	s_lshr_b32 s74, s74, 3
	s_lshl_b32 s74, s74, 14
	v_xor_b32_e32 v143, s75, v243
	v_lshl_add_u32 v143, v143, 4, v142
	v_add_u32_e32 v223, s74, v143
	s_add_u32 s74, s0, 3
	s_and_b32 s75, s74, 7
	s_lshl_b32 s75, s75, 1
	s_lshr_b32 s74, s74, 3
	s_lshl_b32 s74, s74, 14
	v_xor_b32_e32 v143, s75, v243
	v_lshl_add_u32 v143, v143, 4, v142
	v_add_u32_e32 v224, s74, v143
	s_add_u32 s74, s0, 4
	s_and_b32 s75, s74, 7
	s_lshl_b32 s75, s75, 1
	s_lshr_b32 s74, s74, 3
	s_lshl_b32 s74, s74, 14
	v_xor_b32_e32 v143, s75, v243
	v_lshl_add_u32 v143, v143, 4, v142
	v_add_u32_e32 v225, s74, v143
	s_add_u32 s74, s0, 5
	s_and_b32 s75, s74, 7
	s_lshl_b32 s75, s75, 1
	s_lshr_b32 s74, s74, 3
	s_lshl_b32 s74, s74, 14
	v_xor_b32_e32 v143, s75, v243
	v_lshl_add_u32 v143, v143, 4, v142
	v_add_u32_e32 v226, s74, v143
	s_add_u32 s74, s0, 6
	s_and_b32 s75, s74, 7
	s_lshl_b32 s75, s75, 1
	s_lshr_b32 s74, s74, 3
	s_lshl_b32 s74, s74, 14
	v_xor_b32_e32 v143, s75, v243
	v_lshl_add_u32 v143, v143, 4, v142
	v_add_u32_e32 v227, s74, v143
	s_add_u32 s74, s0, 7
	s_and_b32 s75, s74, 7
	s_lshl_b32 s75, s75, 1
	s_lshr_b32 s74, s74, 3
	s_lshl_b32 s74, s74, 14
	v_xor_b32_e32 v143, s75, v243
	v_lshl_add_u32 v143, v143, 4, v142
	v_add_u32_e32 v228, s74, v143
	s_add_u32 s74, s0, 8
	s_and_b32 s75, s74, 7
	s_lshl_b32 s75, s75, 1
	s_lshr_b32 s74, s74, 3
	s_lshl_b32 s74, s74, 14
	v_xor_b32_e32 v143, s75, v243
	v_lshl_add_u32 v143, v143, 4, v142
	v_add_u32_e32 v229, s74, v143
	s_and_b32 s74, s0, 1
	s_lshl_b32 s74, s74, 2
	v_add_u32_e32 v142, s74, v242
	v_and_b32_e32 v143, 7, v141
	v_xor_b32_e32 v142, v142, v143
	v_lshlrev_b32_e32 v142, 4, v142
	v_lshrrev_b32_e32 v143, 3, v141
	s_lshl_b32 s74, s0, 3
	v_add_u32_e32 v143, s74, v143
	v_lshl_add_u32 v232, v143, 7, v142
	v_add_u32_e32 v233, 0x2000, v232
	s_and_b32 s74, s0, 3
	s_lshl_b32 s74, s74, 2
	v_add_u32_e32 v142, s74, v242
	v_xor_b32_e32 v142, v142, v241
	v_lshlrev_b32_e32 v142, 4, v142
	s_lshl_b32 s74, s0, 2
	v_add_u32_e32 v143, s74, v242
	v_lshl_add_u32 v234, v143, 15, v142
	v_add_u32_e32 v235, 0x100000, v234
	s_lshl_b32 s74, s0, 4
	v_add_u32_e32 v142, s74, v241
	v_lshlrev_b32_e32 v142, 0, v142
	v_lshlrev_b32_e32 v238, 2, v142
	v_lshlrev_b32_e32 v142, 7, v142
	v_lshl_add_u32 v236, v242, 4, v142
	v_lshl_add_u32 v237, v242, 3, v142
	v_xor_b32_e32 v142, 16, v141
	v_lshlrev_b32_e32 v239, 2, v142
	v_xor_b32_e32 v142, 32, v141
	v_lshlrev_b32_e32 v240, 2, v142
	s_add_u32 s74, s2, 1
	v_cvt_f32_u32_e32 v142, s74
	v_mul_f32_e32 v142, 0xc1000000, v142
	v_mul_f32_e32 v142, 0x3caaaaab, v142
	v_exp_f32_e32 v142, v142
	v_lshlrev_b32_e32 v144, 2, v242
	v_sub_u32_e32 v145, v241, v144
	v_mul_f32_e32 v142, 0x3f800000, v142
	v_add_u32_e32 v145, 0x80, v145
	v_mul_f32_e32 v142, 0x3fb8aa3b, v142
	v_cvt_f32_i32_e32 v145, v145
	s_nop 0
	v_mul_f32_e64 v143, -v142, v145
	v_fmamk_f32 v185, v142, 0x0, v143
	v_fmamk_f32 v186, v142, 0x3f800000, v143
	v_fmamk_f32 v187, v142, 0x40000000, v143
	v_fmamk_f32 v188, v142, 0x40400000, v143
	v_fmamk_f32 v189, v142, 0x41800000, v143
	v_fmamk_f32 v190, v142, 0x41880000, v143
	v_fmamk_f32 v191, v142, 0x41900000, v143
	v_fmamk_f32 v192, v142, 0x41980000, v143
	v_fmamk_f32 v193, v142, 0x42000000, v143
	v_fmamk_f32 v194, v142, 0x42040000, v143
	v_fmamk_f32 v195, v142, 0x42080000, v143
	v_fmamk_f32 v196, v142, 0x420c0000, v143
	v_fmamk_f32 v197, v142, 0x42400000, v143
	v_fmamk_f32 v198, v142, 0x42440000, v143
	v_fmamk_f32 v199, v142, 0x42480000, v143
	v_fmamk_f32 v200, v142, 0x424c0000, v143
	v_fmamk_f32 v201, v142, 0x42800000, v143
	v_fmamk_f32 v202, v142, 0x42820000, v143
	v_fmamk_f32 v203, v142, 0x42840000, v143
	v_fmamk_f32 v204, v142, 0x42860000, v143
	v_fmamk_f32 v205, v142, 0x42a00000, v143
	v_fmamk_f32 v206, v142, 0x42a20000, v143
	v_fmamk_f32 v207, v142, 0x42a40000, v143
	v_fmamk_f32 v208, v142, 0x42a60000, v143
	v_fmamk_f32 v209, v142, 0x42c00000, v143
	v_fmamk_f32 v210, v142, 0x42c20000, v143
	v_fmamk_f32 v211, v142, 0x42c40000, v143
	v_fmamk_f32 v212, v142, 0x42c60000, v143
	v_fmamk_f32 v213, v142, 0x42e00000, v143
	v_fmamk_f32 v214, v142, 0x42e20000, v143
	v_fmamk_f32 v215, v142, 0x42e40000, v143
	v_fmamk_f32 v216, v142, 0x42e60000, v143
	v_fmamk_f32 v217, v142, 0x43000000, v143
	v_fmamk_f32 v218, v142, 0x43010000, v143
	v_fmamk_f32 v219, v142, 0x43020000, v143
	v_fmamk_f32 v220, v142, 0x43030000, v143
	v_add_u32_e32 v145, 0, v144
	v_cmp_lt_u32_e32 vcc, v145, v241
	s_nop 1
	v_cndmask_b32_e32 v185, v185, v244, vcc
	v_cmp_gt_u32_e32 vcc, v145, v241
	s_nop 1
	v_cndmask_b32_e32 v217, v217, v244, vcc
	v_add_u32_e32 v145, 1, v144
	v_cmp_lt_u32_e32 vcc, v145, v241
	s_nop 1
	v_cndmask_b32_e32 v186, v186, v244, vcc
	v_cmp_gt_u32_e32 vcc, v145, v241
	s_nop 1
	v_cndmask_b32_e32 v218, v218, v244, vcc
	v_add_u32_e32 v145, 2, v144
	v_cmp_lt_u32_e32 vcc, v145, v241
	s_nop 1
	v_cndmask_b32_e32 v187, v187, v244, vcc
	v_cmp_gt_u32_e32 vcc, v145, v241
	s_nop 1
	v_cndmask_b32_e32 v219, v219, v244, vcc
	v_add_u32_e32 v145, 3, v144
	v_cmp_lt_u32_e32 vcc, v145, v241
	s_nop 1
	v_cndmask_b32_e32 v188, v188, v244, vcc
	v_cmp_gt_u32_e32 vcc, v145, v241
	s_nop 1
	v_cndmask_b32_e32 v220, v220, v244, vcc
	s_lshl_b32 s74, s4, 7
	s_add_u32 s74, s74, s5
	s_lshl_b32 s75, s74, 7
	s_add_u32 s10, s30, s75
	s_addc_u32 s11, s31, 0
	s_add_u32 s86, s34, s75
	s_addc_u32 s87, s35, 0
	s_lshl_b32 s75, s74, 2
	s_add_u32 s88, s58, s75
	s_addc_u32 s89, s59, 0
	global_load_dwordx4 v[96:99], v236, s[10:11]
	global_load_dwordx4 v[100:103], v236, s[10:11] offset:64
	s_mov_b32 s7, 0
	s_nop 0
	s_nop 0
	s_nop 0
